# P1 deferred weight conversion: the raw f32 weight reads (read once) are non-temporal
# baseline (speedup 1.0000x reference)
; __device__ __forceinline__ void p0_transpose_item(const float* __restrict__ W, int K, int N, bf16* __restrict__ WT, int mode, const float* __restrict__ kscale, int item, int lane) {
;     ...
;     const float* src = W + (size_t)k0 * N + n0 + lane;
;     float v[64];
; #pragma unroll
;     for (int i = 0; i < 64; ++i) v[i] = src[(size_t)i * N];
;     __device__ __forceinline__ void convert(int r, int lane) const {
;         if (r < I_OUT) { p0_transpose_item(w_out, DM, DM, Wout_t, 0, nullptr, r, lane); return; } r -= I_OUT;
;         if (r < I_G) { p0_transpose_item(w_gate, DM, FF, Wgu_t, 1, kscale, r, lane); return; } r -= I_G;
;         if (r < I_G) { p0_transpose_item(w_up, DM, FF, Wgu_t, 2, kscale, r, lane); return; } r -= I_G;
;         p0_transpose_item(w_down, FF, DM, Wdn_t, 0, nullptr, r, lane);
;     }
;     __device__ __forceinline__ void done(const pg8::Unit&) const {
;         if (nxt < NITEMS) { convert(nxt, (int)(threadIdx.x & 63)); nxt += ngw; }
.Lp1_cv_noks_u:
	global_load_dword v128, v196, s[48:49] nt
	s_add_u32 s48, s48, s46
	s_addc_u32 s49, s49, 0
	global_load_dword v129, v196, s[48:49] nt
	s_add_u32 s48, s48, s46
	s_addc_u32 s49, s49, 0
	global_load_dword v130, v196, s[48:49] nt
	s_add_u32 s48, s48, s46
	s_addc_u32 s49, s49, 0
	global_load_dword v131, v196, s[48:49] nt
	s_add_u32 s48, s48, s46
	s_addc_u32 s49, s49, 0
	global_load_dword v132, v196, s[48:49] nt
	s_add_u32 s48, s48, s46
	s_addc_u32 s49, s49, 0
	global_load_dword v133, v196, s[48:49] nt
	s_add_u32 s48, s48, s46
	s_addc_u32 s49, s49, 0
	global_load_dword v134, v196, s[48:49] nt
	s_add_u32 s48, s48, s46
	s_addc_u32 s49, s49, 0
	global_load_dword v135, v196, s[48:49] nt
	s_add_u32 s48, s48, s46
	s_addc_u32 s49, s49, 0
	global_load_dword v136, v196, s[48:49] nt
	s_add_u32 s48, s48, s46
	s_addc_u32 s49, s49, 0
	global_load_dword v137, v196, s[48:49] nt
	s_add_u32 s48, s48, s46
	s_addc_u32 s49, s49, 0
	global_load_dword v138, v196, s[48:49] nt
	s_add_u32 s48, s48, s46
	s_addc_u32 s49, s49, 0
	global_load_dword v139, v196, s[48:49] nt
	s_add_u32 s48, s48, s46
	s_addc_u32 s49, s49, 0
	global_load_dword v140, v196, s[48:49] nt
	s_add_u32 s48, s48, s46
	s_addc_u32 s49, s49, 0
	global_load_dword v141, v196, s[48:49] nt
	s_add_u32 s48, s48, s46
	s_addc_u32 s49, s49, 0
	global_load_dword v142, v196, s[48:49] nt
	s_add_u32 s48, s48, s46
	s_addc_u32 s49, s49, 0
	global_load_dword v143, v196, s[48:49] nt
	s_add_u32 s48, s48, s46
	s_addc_u32 s49, s49, 0
	global_load_dword v144, v196, s[48:49] nt
	s_add_u32 s48, s48, s46
	s_addc_u32 s49, s49, 0
	global_load_dword v145, v196, s[48:49] nt
	s_add_u32 s48, s48, s46
	s_addc_u32 s49, s49, 0
	global_load_dword v146, v196, s[48:49] nt
	s_add_u32 s48, s48, s46
	s_addc_u32 s49, s49, 0
	global_load_dword v147, v196, s[48:49] nt
	s_add_u32 s48, s48, s46
	s_addc_u32 s49, s49, 0
	global_load_dword v148, v196, s[48:49] nt
	s_add_u32 s48, s48, s46
	s_addc_u32 s49, s49, 0
	global_load_dword v149, v196, s[48:49] nt
	s_add_u32 s48, s48, s46
	s_addc_u32 s49, s49, 0
	global_load_dword v150, v196, s[48:49] nt
	s_add_u32 s48, s48, s46
	s_addc_u32 s49, s49, 0
	global_load_dword v151, v196, s[48:49] nt
	s_add_u32 s48, s48, s46
	s_addc_u32 s49, s49, 0
	global_load_dword v152, v196, s[48:49] nt
	s_add_u32 s48, s48, s46
	s_addc_u32 s49, s49, 0
	global_load_dword v153, v196, s[48:49] nt
	s_add_u32 s48, s48, s46
	s_addc_u32 s49, s49, 0
	global_load_dword v154, v196, s[48:49] nt
	s_add_u32 s48, s48, s46
	s_addc_u32 s49, s49, 0
	global_load_dword v155, v196, s[48:49] nt
	s_add_u32 s48, s48, s46
	s_addc_u32 s49, s49, 0
	global_load_dword v156, v196, s[48:49] nt
	s_add_u32 s48, s48, s46
	s_addc_u32 s49, s49, 0
	global_load_dword v157, v196, s[48:49] nt
	s_add_u32 s48, s48, s46
	s_addc_u32 s49, s49, 0
	global_load_dword v158, v196, s[48:49] nt
	s_add_u32 s48, s48, s46
	s_addc_u32 s49, s49, 0
	global_load_dword v159, v196, s[48:49] nt
	s_add_u32 s48, s48, s46
	s_addc_u32 s49, s49, 0
	global_load_dword v160, v196, s[48:49] nt
	s_add_u32 s48, s48, s46
	s_addc_u32 s49, s49, 0
	global_load_dword v161, v196, s[48:49] nt
	s_add_u32 s48, s48, s46
	s_addc_u32 s49, s49, 0
	global_load_dword v162, v196, s[48:49] nt
	s_add_u32 s48, s48, s46
	s_addc_u32 s49, s49, 0
	global_load_dword v163, v196, s[48:49] nt
	s_add_u32 s48, s48, s46
	s_addc_u32 s49, s49, 0
	global_load_dword v164, v196, s[48:49] nt
	s_add_u32 s48, s48, s46
	s_addc_u32 s49, s49, 0
	global_load_dword v165, v196, s[48:49] nt
	s_add_u32 s48, s48, s46
	s_addc_u32 s49, s49, 0
	global_load_dword v166, v196, s[48:49] nt
	s_add_u32 s48, s48, s46
	s_addc_u32 s49, s49, 0
	global_load_dword v167, v196, s[48:49] nt
	s_add_u32 s48, s48, s46
	s_addc_u32 s49, s49, 0
	global_load_dword v168, v196, s[48:49] nt
	s_add_u32 s48, s48, s46
	s_addc_u32 s49, s49, 0
	global_load_dword v169, v196, s[48:49] nt
	s_add_u32 s48, s48, s46
	s_addc_u32 s49, s49, 0
	global_load_dword v170, v196, s[48:49] nt
	s_add_u32 s48, s48, s46
	s_addc_u32 s49, s49, 0
	global_load_dword v171, v196, s[48:49] nt
	s_add_u32 s48, s48, s46
	s_addc_u32 s49, s49, 0
	global_load_dword v172, v196, s[48:49] nt
	s_add_u32 s48, s48, s46
	s_addc_u32 s49, s49, 0
	global_load_dword v173, v196, s[48:49] nt
	s_add_u32 s48, s48, s46
	s_addc_u32 s49, s49, 0
	global_load_dword v174, v196, s[48:49] nt
	s_add_u32 s48, s48, s46
	s_addc_u32 s49, s49, 0
	global_load_dword v175, v196, s[48:49] nt
	s_add_u32 s48, s48, s46
	s_addc_u32 s49, s49, 0
	global_load_dword v176, v196, s[48:49] nt
	s_add_u32 s48, s48, s46
	s_addc_u32 s49, s49, 0
	global_load_dword v177, v196, s[48:49] nt
	s_add_u32 s48, s48, s46
	s_addc_u32 s49, s49, 0
	global_load_dword v178, v196, s[48:49] nt
	s_add_u32 s48, s48, s46
	s_addc_u32 s49, s49, 0
	global_load_dword v179, v196, s[48:49] nt
	s_add_u32 s48, s48, s46
	s_addc_u32 s49, s49, 0
	global_load_dword v180, v196, s[48:49] nt
	s_add_u32 s48, s48, s46
	s_addc_u32 s49, s49, 0
	global_load_dword v181, v196, s[48:49] nt
	s_add_u32 s48, s48, s46
	s_addc_u32 s49, s49, 0
	global_load_dword v182, v196, s[48:49] nt
	s_add_u32 s48, s48, s46
	s_addc_u32 s49, s49, 0
	global_load_dword v183, v196, s[48:49] nt
	s_add_u32 s48, s48, s46
	s_addc_u32 s49, s49, 0
	global_load_dword v188, v196, s[48:49] nt
	s_add_u32 s48, s48, s46
	s_addc_u32 s49, s49, 0
	global_load_dword v189, v196, s[48:49] nt
	s_add_u32 s48, s48, s46
	s_addc_u32 s49, s49, 0
	global_load_dword v190, v196, s[48:49] nt
	s_add_u32 s48, s48, s46
	s_addc_u32 s49, s49, 0
	global_load_dword v191, v196, s[48:49] nt
	s_add_u32 s48, s48, s46
	s_addc_u32 s49, s49, 0
	global_load_dword v192, v196, s[48:49] nt
	s_add_u32 s48, s48, s46
	s_addc_u32 s49, s49, 0
	global_load_dword v193, v196, s[48:49] nt
	s_add_u32 s48, s48, s46
	s_addc_u32 s49, s49, 0
	global_load_dword v194, v196, s[48:49] nt
	s_add_u32 s48, s48, s46
	s_addc_u32 s49, s49, 0
	global_load_dword v195, v196, s[48:49] nt
